# w_in narrow strip tile: waves 1-3 (zero-padded columns only) skip their weight loads and MFMAs
# baseline (speedup 1.0000x reference)
.Lg2_win_nodma_3:
	s_cmp_lg_u32 s70, 0
	s_cbranch_scc1 .Lg2_win_sk3_0
	global_load_dwordx4 v[184:187], v160, s[58:59] offset:0
	global_load_dwordx4 v[188:191], v160, s[58:59] offset:1024
	global_load_dwordx4 v[192:195], v161, s[58:59] offset:0
	global_load_dwordx4 v[196:199], v161, s[58:59] offset:1024
.Lg2_win_sk3_0:
	v_mov_b32_e32 v0, 0
	v_mov_b32_e32 v1, 0
	v_mov_b32_e32 v2, 0
	v_mov_b32_e32 v3, 0
	v_mov_b32_e32 v4, 0
	v_mov_b32_e32 v5, 0
	v_mov_b32_e32 v6, 0
	v_mov_b32_e32 v7, 0
	v_mov_b32_e32 v8, 0
	v_mov_b32_e32 v9, 0
	v_mov_b32_e32 v10, 0
	v_mov_b32_e32 v11, 0
	v_mov_b32_e32 v12, 0
	v_mov_b32_e32 v13, 0
	v_mov_b32_e32 v14, 0
	v_mov_b32_e32 v15, 0
	v_mov_b32_e32 v16, 0
	v_mov_b32_e32 v17, 0
	v_mov_b32_e32 v18, 0
	v_mov_b32_e32 v19, 0
	v_mov_b32_e32 v20, 0
	v_mov_b32_e32 v21, 0
	v_mov_b32_e32 v22, 0
	v_mov_b32_e32 v23, 0
	s_mov_b32 s63, 0

.Lg2_win_nodma_4:
	s_cmp_lg_u32 s70, 0
	s_cbranch_scc1 .Lg2_win_sk3_1
	global_load_dwordx4 v[200:203], v160, s[58:59] offset:0
	global_load_dwordx4 v[204:207], v160, s[58:59] offset:1024
	global_load_dwordx4 v[208:211], v161, s[58:59] offset:0
	global_load_dwordx4 v[240:243], v161, s[58:59] offset:1024
.Lg2_win_sk3_1:
	s_cmp_lg_u32 s70, 0
	s_cbranch_scc1 .Lg2_win_sk3_2
	ds_read_b128 v[136:139], v156 offset:0
	ds_read_b128 v[140:143], v156 offset:2048
	ds_read_b128 v[144:147], v156 offset:4096
	ds_read_b128 v[164:167], v157 offset:0
	ds_read_b128 v[168:171], v157 offset:2048
	ds_read_b128 v[172:175], v157 offset:4096
	s_waitcnt lgkmcnt(3)
	v_mfma_f32_16x16x32_bf16 v[0:3], v[184:187], v[136:139], v[0:3]
	v_mfma_f32_16x16x32_bf16 v[4:7], v[192:195], v[136:139], v[4:7]
	v_mfma_f32_16x16x32_bf16 v[8:11], v[184:187], v[140:143], v[8:11]
	v_mfma_f32_16x16x32_bf16 v[12:15], v[192:195], v[140:143], v[12:15]
	v_mfma_f32_16x16x32_bf16 v[16:19], v[184:187], v[144:147], v[16:19]
	v_mfma_f32_16x16x32_bf16 v[20:23], v[192:195], v[144:147], v[20:23]
	s_waitcnt lgkmcnt(0)
	v_mfma_f32_16x16x32_bf16 v[0:3], v[188:191], v[164:167], v[0:3]
	v_mfma_f32_16x16x32_bf16 v[4:7], v[196:199], v[164:167], v[4:7]
	v_mfma_f32_16x16x32_bf16 v[8:11], v[188:191], v[168:171], v[8:11]
	v_mfma_f32_16x16x32_bf16 v[12:15], v[196:199], v[168:171], v[12:15]
	v_mfma_f32_16x16x32_bf16 v[16:19], v[188:191], v[172:175], v[16:19]
	v_mfma_f32_16x16x32_bf16 v[20:23], v[196:199], v[172:175], v[20:23]
.Lg2_win_sk3_2:
	s_waitcnt vmcnt(0)
	s_barrier
	s_cmp_ge_u32 s63, 14
	s_cbranch_scc1 .Lg2_win_noissue3
	s_add_u32 s56, s56, 0x80
	s_addc_u32 s57, s57, 0
	s_add_u32 s58, s58, 0x800
	s_addc_u32 s59, s59, 0
	s_add_u32 m0, s62, 0x0
	s_add_u32 s4, s56, 0x0
	s_addc_u32 s5, s57, 0
	global_load_lds_dwordx4 v162, s[4:5]
	s_cmp_gt_u32 s70, 1
	s_cbranch_scc1 .Lg2_win_nodma_5
	s_add_u32 m0, s62, 0x1000
	s_add_u32 s4, s56, 0x10000
	s_addc_u32 s5, s57, 0
	global_load_lds_dwordx4 v162, s[4:5]

.Lg2_win_sk3_3:
.Lg2_win_noissue3:
	s_cmp_lg_u32 s70, 0
	s_cbranch_scc1 .Lg2_win_sk3_4
	ds_read_b128 v[136:139], v158 offset:0
	ds_read_b128 v[140:143], v158 offset:2048
	ds_read_b128 v[144:147], v158 offset:4096
	ds_read_b128 v[164:167], v159 offset:0
	ds_read_b128 v[168:171], v159 offset:2048
	ds_read_b128 v[172:175], v159 offset:4096
	s_waitcnt lgkmcnt(3)
	v_mfma_f32_16x16x32_bf16 v[0:3], v[200:203], v[136:139], v[0:3]
	v_mfma_f32_16x16x32_bf16 v[4:7], v[208:211], v[136:139], v[4:7]
	v_mfma_f32_16x16x32_bf16 v[8:11], v[200:203], v[140:143], v[8:11]
	v_mfma_f32_16x16x32_bf16 v[12:15], v[208:211], v[140:143], v[12:15]
	v_mfma_f32_16x16x32_bf16 v[16:19], v[200:203], v[144:147], v[16:19]
	v_mfma_f32_16x16x32_bf16 v[20:23], v[208:211], v[144:147], v[20:23]
	s_waitcnt lgkmcnt(0)
	v_mfma_f32_16x16x32_bf16 v[0:3], v[204:207], v[164:167], v[0:3]
	v_mfma_f32_16x16x32_bf16 v[4:7], v[240:243], v[164:167], v[4:7]
	v_mfma_f32_16x16x32_bf16 v[8:11], v[204:207], v[168:171], v[8:11]
	v_mfma_f32_16x16x32_bf16 v[12:15], v[240:243], v[168:171], v[12:15]
	v_mfma_f32_16x16x32_bf16 v[16:19], v[204:207], v[172:175], v[16:19]
	v_mfma_f32_16x16x32_bf16 v[20:23], v[240:243], v[172:175], v[20:23]
.Lg2_win_sk3_4:
	s_add_i32 s63, s63, 2
	s_cmp_lt_u32 s63, 16
	s_cbranch_scc1 .Lg2_win_loop3
	s_branch .Lg2_win_epiK
.Lg2_win_k2:
	s_add_u32 m0, s62, 0x0
	s_add_u32 s4, s56, 0x0
	s_addc_u32 s5, s57, 0
	global_load_lds_dwordx4 v162, s[4:5]
	s_cmp_lg_u32 s70, 0
	s_cbranch_scc1 .Lg2_win_sk2_5
	global_load_dwordx4 v[184:187], v160, s[58:59] offset:0
	global_load_dwordx4 v[188:191], v160, s[58:59] offset:1024
	global_load_dwordx4 v[192:195], v161, s[58:59] offset:0
	global_load_dwordx4 v[196:199], v161, s[58:59] offset:1024
.Lg2_win_sk2_5:
	v_mov_b32_e32 v0, 0
	v_mov_b32_e32 v1, 0
	v_mov_b32_e32 v2, 0
	v_mov_b32_e32 v3, 0
	v_mov_b32_e32 v4, 0
	v_mov_b32_e32 v5, 0
	v_mov_b32_e32 v6, 0
	v_mov_b32_e32 v7, 0
	v_mov_b32_e32 v8, 0
	v_mov_b32_e32 v9, 0
	v_mov_b32_e32 v10, 0
	v_mov_b32_e32 v11, 0
	v_mov_b32_e32 v12, 0
	v_mov_b32_e32 v13, 0
	v_mov_b32_e32 v14, 0
	v_mov_b32_e32 v15, 0
	s_mov_b32 s63, 0
.Lg2_win_loop2:
	s_waitcnt vmcnt(0)
	s_barrier
	s_add_u32 s56, s56, 0x80
	s_addc_u32 s57, s57, 0
	s_add_u32 s58, s58, 0x800
	s_addc_u32 s59, s59, 0
	s_add_u32 m0, s62, 0x8800
	s_add_u32 s4, s56, 0x0
	s_addc_u32 s5, s57, 0
	global_load_lds_dwordx4 v162, s[4:5]
	s_cmp_lg_u32 s70, 0
	s_cbranch_scc1 .Lg2_win_sk2_6
	global_load_dwordx4 v[200:203], v160, s[58:59] offset:0
	global_load_dwordx4 v[204:207], v160, s[58:59] offset:1024
	global_load_dwordx4 v[208:211], v161, s[58:59] offset:0
	global_load_dwordx4 v[240:243], v161, s[58:59] offset:1024
.Lg2_win_sk2_6:
	s_cmp_lg_u32 s70, 0
	s_cbranch_scc1 .Lg2_win_sk2_7
	ds_read_b128 v[136:139], v156 offset:0
	ds_read_b128 v[140:143], v156 offset:2048
	ds_read_b128 v[164:167], v157 offset:0
	ds_read_b128 v[168:171], v157 offset:2048
	s_waitcnt lgkmcnt(2)
	v_mfma_f32_16x16x32_bf16 v[0:3], v[184:187], v[136:139], v[0:3]
	v_mfma_f32_16x16x32_bf16 v[4:7], v[192:195], v[136:139], v[4:7]
	v_mfma_f32_16x16x32_bf16 v[8:11], v[184:187], v[140:143], v[8:11]
	v_mfma_f32_16x16x32_bf16 v[12:15], v[192:195], v[140:143], v[12:15]
	s_waitcnt lgkmcnt(0)
	v_mfma_f32_16x16x32_bf16 v[0:3], v[188:191], v[164:167], v[0:3]
	v_mfma_f32_16x16x32_bf16 v[4:7], v[196:199], v[164:167], v[4:7]
	v_mfma_f32_16x16x32_bf16 v[8:11], v[188:191], v[168:171], v[8:11]
	v_mfma_f32_16x16x32_bf16 v[12:15], v[196:199], v[168:171], v[12:15]
.Lg2_win_sk2_7:
	s_waitcnt vmcnt(0)
	s_barrier
	s_cmp_ge_u32 s63, 14
	s_cbranch_scc1 .Lg2_win_noissue2
	s_add_u32 s56, s56, 0x80
	s_addc_u32 s57, s57, 0
	s_add_u32 s58, s58, 0x800
	s_addc_u32 s59, s59, 0
	s_add_u32 m0, s62, 0x0
	s_add_u32 s4, s56, 0x0
	s_addc_u32 s5, s57, 0
	global_load_lds_dwordx4 v162, s[4:5]
	s_cmp_lg_u32 s70, 0
	s_cbranch_scc1 .Lg2_win_sk2_8
	global_load_dwordx4 v[184:187], v160, s[58:59] offset:0
	global_load_dwordx4 v[188:191], v160, s[58:59] offset:1024
	global_load_dwordx4 v[192:195], v161, s[58:59] offset:0
	global_load_dwordx4 v[196:199], v161, s[58:59] offset:1024
.Lg2_win_sk2_8:
.Lg2_win_noissue2:
	s_cmp_lg_u32 s70, 0
	s_cbranch_scc1 .Lg2_win_sk2_9
	ds_read_b128 v[136:139], v158 offset:0
	ds_read_b128 v[140:143], v158 offset:2048
	ds_read_b128 v[164:167], v159 offset:0
	ds_read_b128 v[168:171], v159 offset:2048
	s_waitcnt lgkmcnt(2)
	v_mfma_f32_16x16x32_bf16 v[0:3], v[200:203], v[136:139], v[0:3]
	v_mfma_f32_16x16x32_bf16 v[4:7], v[208:211], v[136:139], v[4:7]
	v_mfma_f32_16x16x32_bf16 v[8:11], v[200:203], v[140:143], v[8:11]
	v_mfma_f32_16x16x32_bf16 v[12:15], v[208:211], v[140:143], v[12:15]
	s_waitcnt lgkmcnt(0)
	v_mfma_f32_16x16x32_bf16 v[0:3], v[204:207], v[164:167], v[0:3]
	v_mfma_f32_16x16x32_bf16 v[4:7], v[240:243], v[164:167], v[4:7]
	v_mfma_f32_16x16x32_bf16 v[8:11], v[204:207], v[168:171], v[8:11]
	v_mfma_f32_16x16x32_bf16 v[12:15], v[240:243], v[168:171], v[12:15]
